# unit-boundary counted waits extended to the QKV loops (vmcnt(23) in the first K-tile after an epilogue)
# baseline (speedup 1.0000x reference)
; #define PG8_STAGE(bufoff, gbase, voff) do { _Pragma("unroll") for (int _i = 0; _i < 2; ++_i) \
;         __builtin_amdgcn_global_load_lds((const unsigned*)((const char*)(gbase) + (voff)[_i]), (PG8_LAS unsigned*)(lds + (bufoff) + ldsw + _i * 8192), 16, 0, 0); } while (0)
; #define PG8_WAIT_V(n) asm volatile("s_waitcnt vmcnt(" #n ")" ::: "memory")
; #define PG8_BAR __builtin_amdgcn_s_barrier()
; template <class Epi, class Sched, bool ALIGN_EPI = false, bool SP2 = false>
; __device__ __forceinline__ void gemm_phase(PG8_LAS unsigned char* lds, const Gemm g, const Sched& S, const Epi& E) {
;     ...
;     for (int i = 0; i < 2; ++i) { int R, C; stage_rc(tid * 16 + i * 8192, R, C); const int Rb = Epi::PERM ? ((R & ~31) + perm32(R & 31)) : R;
;         voffA[i] = (unsigned)(R * K + C) * 2u; voffB[i] = (unsigned)(Rb * K + C) * 2u; }
;     const size_t kstep = (size_t)(BK * 2);
;     const size_t hstep = (size_t)HALF * K * 2;
;     const size_t tstep = 2 * hstep;
;     const unsigned ldsw = (unsigned)wid * 1024u;
;     const int aoff = lds_byte(wr * 64 + fr, fq * 8), boff = lds_byte(wc * 32 + fr, fq * 8);
;     ...
;     if constexpr (SP2) {
;         PG8_STAGE(PG8_SB(0, 0), cB, voffB); PG8_STAGE(PG8_SB(0, 1), cB + hstep, voffB); PG8_STAGE(PG8_SA(0, 0), cA, voffA); PG8_STAGE(PG8_SA(0, 1), cA + hstep, voffA);
;         if (wr == 1) PG8_BAR;
;         PG8_WAIT_V(2); PG8_BAR;
;         PG8_STAGE(PG8_SB(1, 0), cB + kstep, voffB); PG8_STAGE(PG8_SA(1, 0), cA + kstep, voffA); PG8_STAGE(PG8_SB(1, 1), cB + hstep + kstep, voffB);
;         PG8_WAIT_V(6); PG8_BAR;
.LBB0_179:
	v_lshrrev_b32_e32 v13, 1, v12
	v_and_b32_e32 v190, 24, v13
	v_and_b32_e32 v1, 15, v12
	v_lshlrev_b32_e32 v13, 1, v190
	v_lshlrev_b32_e32 v12, 2, v12
	v_lshl_or_b32 v13, v1, 6, v13
	s_lshl_b32 s13, s16, 13
	v_and_b32_e32 v12, 32, v12
	v_readlane_b32 s24, v254, 43
	v_bitop3_b32 v22, v13, s13, v12 bitop3:0xde
	s_lshl_b32 s13, s14, 5
	v_mov_b32_e32 v171, v0
	v_readlane_b32 s25, v254, 44
	s_and_b32 s33, s13, 0x60
	s_add_i32 m0, s10, 0x18000
	v_lshl_add_u64 v[2:3], v[2:3], 0, s[34:35]
	v_lshl_add_u64 v[18:19], s[24:25], 0, v[170:171]
	v_mov_b32_e32 v167, v0
	s_lshl_b32 s28, s16, 6
	s_lshl_b32 s13, s33, 7
	s_waitcnt vmcnt(2)
	s_barrier
	global_load_lds_dwordx4 v[2:3], off
	v_lshl_add_u64 v[2:3], v[4:5], 0, s[34:35]
	s_add_i32 m0, s10, 0x1a000
	s_add_i32 s49, s10, 0x8000
	s_add_i32 s58, s10, 0xa000
	v_lshl_add_u64 v[20:21], s[24:25], 0, v[166:167]
	global_load_lds_dwordx4 v[2:3], off
	v_lshl_add_u64 v[2:3], v[18:19], 0, s[34:35]
	s_mov_b32 m0, s49
	s_add_u32 s14, s22, 0x40080
	global_load_lds_dwordx4 v[2:3], off
	v_lshl_add_u64 v[2:3], v[20:21], 0, s[34:35]
	s_mov_b32 m0, s58
	s_addc_u32 s15, s23, 0
	global_load_lds_dwordx4 v[2:3], off
	s_add_i32 m0, s10, 0x1c000
	v_lshl_add_u64 v[2:3], s[14:15], 0, v[168:169]
	global_load_lds_dwordx4 v[2:3], off
	v_lshl_add_u64 v[2:3], s[14:15], 0, v[14:15]
	s_add_i32 m0, s10, 0x1e000
	v_and_b32_e32 v4, 1, v10
	global_load_lds_dwordx4 v[2:3], off
	v_lshlrev_b32_e32 v3, 14, v10
	v_and_b32_e32 v3, 0xffff8000, v3
	v_lshl_add_u32 v3, v9, 11, v3
	s_cmpk_lt_u32 s12, 0x100
	v_lshl_or_b32 v3, v4, 6, v3
	s_cselect_b64 s[14:15], -1, 0
	s_lshl_b32 s12, s16, 9
	v_lshl_add_u32 v172, v11, 1, v3
	v_lshlrev_b32_e32 v3, 14, v6
	s_add_i32 s12, s12, 0
	v_and_b32_e32 v3, 0xffff8000, v3
	s_waitcnt vmcnt(6)
	s_add_i32 s12, s12, 0x20000
	v_lshl_add_u32 v3, v7, 11, v3
	v_and_b32_e32 v4, 1, v6
	v_bitop3_b32 v191, v13, s13, v12 bitop3:0xde
	v_or_b32_e32 v2, s33, v190
	v_lshl_add_u32 v192, v1, 3, s12
	v_lshl_or_b32 v3, v4, 6, v3
	v_readlane_b32 s12, v254, 39
	v_mov_b32_e32 v173, v0
	v_lshl_add_u32 v174, v8, 1, v3
	v_mov_b32_e32 v175, v0
	s_mov_b32 s20, 0
	v_add_u32_e32 v193, 0, v22
	v_lshlrev_b32_e32 v194, 2, v2
	v_readlane_b32 s71, v254, 29
	s_mov_b32 s72, s12
	s_barrier
	v_readlane_b32 s13, v254, 40
	s_mov_b32 s32, 1
	s_branch .LBB0_182

; #define PG8_BAR __builtin_amdgcn_s_barrier()
; template <class Epi, class Sched, bool ALIGN_EPI = false, bool SP2 = false>
; __device__ __forceinline__ void gemm_phase(PG8_LAS unsigned char* lds, const Gemm g, const Sched& S, const Epi& E) {
;     ...
;         if (!has_next) break;
; #pragma unroll
;         for (int a = 0; a < 2; ++a)
; #pragma unroll
;             for (int b = 0; b < 2; ++b)
; #pragma unroll
;                 for (int m = 0; m < 4; ++m)
; #pragma unroll
;                     for (int n = 0; n < 2; ++n) acc[a][b][m][n] = (f32x4){0.f, 0.f, 0.f, 0.f};
;         cur = nxt; cA = nA; cB = nB; ++ui;
;         if constexpr (ALIGN_EPI) { if (wr == 1) PG8_BAR; }
.LBB0_181:
	s_mov_b32 s32, -2
	s_andn2_b64 vcc, exec, s[22:23]
	s_mov_b32 s71, s16
	s_mov_b32 s72, s38
	s_mov_b64 s[22:23], s[42:43]
	s_mov_b64 s[24:25], s[40:41]
	s_mov_b32 s20, s29
	s_cbranch_vccz .LBB0_257

; #define PG8_STAGE(bufoff, gbase, voff) do { _Pragma("unroll") for (int _i = 0; _i < 2; ++_i) \
;         __builtin_amdgcn_global_load_lds((const unsigned*)((const char*)(gbase) + (voff)[_i]), (PG8_LAS unsigned*)(lds + (bufoff) + ldsw + _i * 8192), 16, 0, 0); } while (0)
; #define PG8_LDA(dst, b, h) do { _Pragma("unroll") for (int m = 0; m < 4; ++m) _Pragma("unroll") for (int k = 0; k < 2; ++k) dst[m][k] = *(const PG8_LAS bf16x8*)(lds + PG8_SA(b, h) + aoff + m * 2048 + k * 1024); } while (0)
; #define PG8_LDB(dst, b, h) do { _Pragma("unroll") for (int n = 0; n < 2; ++n) _Pragma("unroll") for (int k = 0; k < 2; ++k) dst[n][k] = *(const PG8_LAS bf16x8*)(lds + PG8_SB(b, h) + boff + n * 2048 + k * 1024); } while (0)
; #define PG8_SCHED __builtin_amdgcn_sched_barrier(0)
; template <class Epi, class Sched, bool ALIGN_EPI = false, bool SP2 = false>
; __device__ __forceinline__ void gemm_phase(PG8_LAS unsigned char* lds, const Gemm g, const Sched& S, const Epi& E) {
;     ...
;             const bool last = (t == nt - 2);
;             const char* a1 = cA + (size_t)(t + 1) * kstep;
;             const char* a2 = last ? nA : cA + (size_t)(t + 2) * kstep; const char* b2 = last ? nB : cB + (size_t)(t + 2) * kstep;
;             const char* a3 = a2 + kstep; const char* b3 = b2 + kstep;
;             if (last && has_next) S.a_ready(nxt);
;             if constexpr (SP2) {
;             PG8_LDB(B0, 0, 0); PG8_LDB(B1, 0, 1); PG8_SCHED; PG8_LDA(At, 0, 0); PG8_STAGE(PG8_SA(1, 1), a1 + hstep, voffA);
.LBB0_185:
	s_add_u32 s12, s50, 0xfffc0080
	s_addc_u32 s13, s51, -1
	s_add_i32 s92, 0, 0x10000
	s_cmp_eq_u32 s83, 12
	s_cselect_b32 s25, s39, s13
	s_cselect_b32 s24, s73, s12
	s_cselect_b32 s23, s17, s82
	s_cselect_b32 s22, s76, s77
	s_add_i32 s12, 0, 0x14000
	v_add_u32_e32 v106, s92, v191
	v_add_u32_e32 v130, s12, v191
	ds_read_b128 v[94:97], v106
	ds_read_b128 v[98:101], v106 offset:1024
	ds_read_b128 v[102:105], v106 offset:2048
	ds_read_b128 v[106:109], v106 offset:3072
	ds_read_b128 v[114:117], v130
	ds_read_b128 v[118:121], v130 offset:1024
	ds_read_b128 v[126:129], v130 offset:2048
	ds_read_b128 v[130:133], v130 offset:3072
	v_lshl_add_u64 v[188:189], s[50:51], 0, v[172:173]
	s_add_i32 m0, s10, 0xc000
	ds_read_b128 v[176:179], v193
	ds_read_b128 v[180:183], v193 offset:1024
	ds_read_b128 v[184:187], v193 offset:2048
	ds_read_b128 v[196:199], v193 offset:3072
	ds_read_b128 v[200:203], v193 offset:4096
	ds_read_b128 v[204:207], v193 offset:5120
	ds_read_b128 v[218:221], v193 offset:6144
	ds_read_b128 v[222:225], v193 offset:7168
	global_load_lds_dwordx4 v[188:189], off
	v_lshl_add_u64 v[188:189], s[50:51], 0, v[174:175]
	s_add_i32 m0, s10, 0xe000
	s_nop 0
	global_load_lds_dwordx4 v[188:189], off
	s_cmp_lg_u32 s12, s32
	s_cbranch_scc1 .Lfw8_185_0
	s_waitcnt vmcnt(23)
	s_branch .Lfwd_185_0

; #define PG8_STAGE(bufoff, gbase, voff) do { _Pragma("unroll") for (int _i = 0; _i < 2; ++_i) \
;         __builtin_amdgcn_global_load_lds((const unsigned*)((const char*)(gbase) + (voff)[_i]), (PG8_LAS unsigned*)(lds + (bufoff) + ldsw + _i * 8192), 16, 0, 0); } while (0)
; #define PG8_LDA(dst, b, h) do { _Pragma("unroll") for (int m = 0; m < 4; ++m) _Pragma("unroll") for (int k = 0; k < 2; ++k) dst[m][k] = *(const PG8_LAS bf16x8*)(lds + PG8_SA(b, h) + aoff + m * 2048 + k * 1024); } while (0)
; #define PG8_MMA(ai, bj, At, Bt) do { __builtin_amdgcn_s_setprio(1); _Pragma("unroll") for (int m = 0; m < 4; ++m) _Pragma("unroll") for (int n = 0; n < 2; ++n) _Pragma("unroll") for (int k = 0; k < 2; ++k) \
;         acc[ai][bj][m][n] = __builtin_amdgcn_mfma_f32_16x16x32_f16(Bt[n][k], At[m][k], acc[ai][bj][m][n], 0, 0, 0); __builtin_amdgcn_s_setprio(0); } while (0)
; #define PG8_WAIT_V(n) asm volatile("s_waitcnt vmcnt(" #n ")" ::: "memory")
; #define PG8_WAIT_L(n) asm volatile("s_waitcnt lgkmcnt(" #n ")" ::: "memory")
; #define PG8_BAR __builtin_amdgcn_s_barrier()
; #define PG8_SCHED __builtin_amdgcn_sched_barrier(0)
; template <class Epi, class Sched, bool ALIGN_EPI = false, bool SP2 = false>
; __device__ __forceinline__ void gemm_phase(PG8_LAS unsigned char* lds, const Gemm g, const Sched& S, const Epi& E) {
;     ...
;             PG8_WAIT_V(8); PG8_WAIT_L(0); PG8_BAR; PG8_MMA(0, 0, At, B0); PG8_MMA(0, 1, At, B1); PG8_BAR; PG8_SCHED;
;             PG8_LDA(At, 0, 1); PG8_STAGE(PG8_SB(0, 0), b2, voffB); PG8_STAGE(PG8_SB(0, 1), b2 + hstep, voffB); PG8_STAGE(PG8_SA(0, 0), a2, voffA);
.Lfwd_185_0:
	s_waitcnt lgkmcnt(0)
	s_barrier
	v_mfma_f32_16x16x32_f16 v[162:165], v[94:97], v[176:179], v[162:165]
	v_mfma_f32_16x16x32_f16 v[158:161], v[102:105], v[176:179], v[158:161]
	v_mfma_f32_16x16x32_f16 v[146:149], v[94:97], v[184:187], v[146:149]
	v_mfma_f32_16x16x32_f16 v[142:145], v[102:105], v[184:187], v[142:145]
	v_mfma_f32_16x16x32_f16 v[122:125], v[94:97], v[200:203], v[122:125]
	v_mfma_f32_16x16x32_f16 v[110:113], v[102:105], v[200:203], v[110:113]
	v_mfma_f32_16x16x32_f16 v[82:85], v[94:97], v[218:221], v[82:85]
	v_mfma_f32_16x16x32_f16 v[78:81], v[102:105], v[218:221], v[78:81]
	v_mfma_f32_16x16x32_f16 v[162:165], v[98:101], v[180:183], v[162:165]
	v_mfma_f32_16x16x32_f16 v[158:161], v[106:109], v[180:183], v[158:161]
	v_mfma_f32_16x16x32_f16 v[146:149], v[98:101], v[196:199], v[146:149]
	v_mfma_f32_16x16x32_f16 v[142:145], v[106:109], v[196:199], v[142:145]
	v_mfma_f32_16x16x32_f16 v[122:125], v[98:101], v[204:207], v[122:125]
	v_mfma_f32_16x16x32_f16 v[110:113], v[106:109], v[204:207], v[110:113]
	v_mfma_f32_16x16x32_f16 v[82:85], v[98:101], v[222:225], v[82:85]
	v_mfma_f32_16x16x32_f16 v[78:81], v[106:109], v[222:225], v[78:81]
	v_mfma_f32_16x16x32_f16 v[154:157], v[114:117], v[176:179], v[154:157]
	v_mfma_f32_16x16x32_f16 v[150:153], v[126:129], v[176:179], v[150:153]
	v_mfma_f32_16x16x32_f16 v[138:141], v[114:117], v[184:187], v[138:141]
	v_mfma_f32_16x16x32_f16 v[134:137], v[126:129], v[184:187], v[134:137]
	v_mfma_f32_16x16x32_f16 v[90:93], v[114:117], v[200:203], v[90:93]
	v_mfma_f32_16x16x32_f16 v[86:89], v[126:129], v[200:203], v[86:89]
	v_mfma_f32_16x16x32_f16 v[74:77], v[114:117], v[218:221], v[74:77]
	v_mfma_f32_16x16x32_f16 v[70:73], v[126:129], v[218:221], v[70:73]
	v_mfma_f32_16x16x32_f16 v[154:157], v[118:121], v[180:183], v[154:157]
	v_mfma_f32_16x16x32_f16 v[150:153], v[130:133], v[180:183], v[150:153]
	v_mfma_f32_16x16x32_f16 v[138:141], v[118:121], v[196:199], v[138:141]
	v_mfma_f32_16x16x32_f16 v[134:137], v[130:133], v[196:199], v[134:137]
	v_mfma_f32_16x16x32_f16 v[90:93], v[118:121], v[204:207], v[90:93]
	v_mfma_f32_16x16x32_f16 v[86:89], v[130:133], v[204:207], v[86:89]
	v_mfma_f32_16x16x32_f16 v[74:77], v[118:121], v[222:225], v[74:77]
	v_mfma_f32_16x16x32_f16 v[70:73], v[130:133], v[222:225], v[70:73]
	s_barrier
	s_add_i32 s13, s92, s5
	v_lshl_add_u64 v[188:189], s[22:23], 0, v[168:169]
	s_mov_b32 m0, s13
	ds_read_b128 v[176:179], v193 offset:16384
	ds_read_b128 v[180:183], v193 offset:17408
	ds_read_b128 v[184:187], v193 offset:18432
	ds_read_b128 v[196:199], v193 offset:19456
	ds_read_b128 v[200:203], v193 offset:20480
	ds_read_b128 v[204:207], v193 offset:21504
	ds_read_b128 v[218:221], v193 offset:22528
	ds_read_b128 v[222:225], v193 offset:23552
	global_load_lds_dwordx4 v[188:189], off
	s_add_i32 m0, s13, 0x2000
	s_add_u32 vcc_lo, s22, 0x40000
	v_lshl_add_u64 v[208:209], s[22:23], 0, v[14:15]
	s_addc_u32 vcc_hi, s23, 0
	s_add_i32 s12, s12, s5
	global_load_lds_dwordx4 v[208:209], off
	v_lshl_add_u64 v[210:211], vcc, 0, v[168:169]
	s_mov_b32 m0, s12
	v_lshl_add_u64 v[212:213], s[24:25], 0, v[166:167]
	global_load_lds_dwordx4 v[210:211], off
	v_lshl_add_u64 v[210:211], vcc, 0, v[14:15]
	s_add_i32 m0, s12, 0x2000
	s_nop 0
	global_load_lds_dwordx4 v[210:211], off
	v_lshl_add_u64 v[210:211], s[24:25], 0, v[170:171]
	s_mov_b32 m0, s10
	s_nop 0
	global_load_lds_dwordx4 v[210:211], off
	s_mov_b32 m0, s11
	s_nop 0
	global_load_lds_dwordx4 v[212:213], off
	s_cmp_lg_u32 s12, s32
	s_cbranch_scc1 .Lfw8_185_1
	s_waitcnt vmcnt(23)
	s_branch .Lfwd_185_1

; #define PG8_STAGE(bufoff, gbase, voff) do { _Pragma("unroll") for (int _i = 0; _i < 2; ++_i) \
;         __builtin_amdgcn_global_load_lds((const unsigned*)((const char*)(gbase) + (voff)[_i]), (PG8_LAS unsigned*)(lds + (bufoff) + ldsw + _i * 8192), 16, 0, 0); } while (0)
; #define PG8_LDA(dst, b, h) do { _Pragma("unroll") for (int m = 0; m < 4; ++m) _Pragma("unroll") for (int k = 0; k < 2; ++k) dst[m][k] = *(const PG8_LAS bf16x8*)(lds + PG8_SA(b, h) + aoff + m * 2048 + k * 1024); } while (0)
; #define PG8_LDB(dst, b, h) do { _Pragma("unroll") for (int n = 0; n < 2; ++n) _Pragma("unroll") for (int k = 0; k < 2; ++k) dst[n][k] = *(const PG8_LAS bf16x8*)(lds + PG8_SB(b, h) + boff + n * 2048 + k * 1024); } while (0)
; #define PG8_MMA(ai, bj, At, Bt) do { __builtin_amdgcn_s_setprio(1); _Pragma("unroll") for (int m = 0; m < 4; ++m) _Pragma("unroll") for (int n = 0; n < 2; ++n) _Pragma("unroll") for (int k = 0; k < 2; ++k) \
;         acc[ai][bj][m][n] = __builtin_amdgcn_mfma_f32_16x16x32_f16(Bt[n][k], At[m][k], acc[ai][bj][m][n], 0, 0, 0); __builtin_amdgcn_s_setprio(0); } while (0)
; #define PG8_WAIT_V(n) asm volatile("s_waitcnt vmcnt(" #n ")" ::: "memory")
; #define PG8_WAIT_L(n) asm volatile("s_waitcnt lgkmcnt(" #n ")" ::: "memory")
; #define PG8_BAR __builtin_amdgcn_s_barrier()
; #define PG8_SCHED __builtin_amdgcn_sched_barrier(0)
; template <class Epi, class Sched, bool ALIGN_EPI = false, bool SP2 = false>
; __device__ __forceinline__ void gemm_phase(PG8_LAS unsigned char* lds, const Gemm g, const Sched& S, const Epi& E) {
;     ...
;             PG8_WAIT_V(8); PG8_WAIT_L(0); PG8_BAR; PG8_MMA(1, 0, At, B0); PG8_MMA(1, 1, At, B1); PG8_BAR; PG8_SCHED;
;             PG8_LDB(B0, 1, 0); PG8_LDB(B1, 1, 1); PG8_SCHED; PG8_LDA(At, 1, 0); PG8_STAGE(PG8_SA(0, 1), a2 + hstep, voffA);
;             PG8_WAIT_V(8); PG8_WAIT_L(0); PG8_BAR; PG8_MMA(0, 0, At, B0); PG8_MMA(0, 1, At, B1); PG8_BAR; PG8_SCHED;
.Lfwd_185_1:
	s_waitcnt lgkmcnt(0)
	s_barrier
	v_mfma_f32_16x16x32_f16 v[66:69], v[94:97], v[176:179], v[66:69]
	v_mfma_f32_16x16x32_f16 v[62:65], v[102:105], v[176:179], v[62:65]
	v_mfma_f32_16x16x32_f16 v[50:53], v[94:97], v[184:187], v[50:53]
	v_mfma_f32_16x16x32_f16 v[46:49], v[102:105], v[184:187], v[46:49]
	v_mfma_f32_16x16x32_f16 v[34:37], v[94:97], v[200:203], v[34:37]
	v_mfma_f32_16x16x32_f16 v[30:33], v[102:105], v[200:203], v[30:33]
	v_mfma_f32_16x16x32_f16 v[18:21], v[94:97], v[218:221], v[18:21]
	v_mfma_f32_16x16x32_f16 v[10:13], v[102:105], v[218:221], v[10:13]
	v_mfma_f32_16x16x32_f16 v[66:69], v[98:101], v[180:183], v[66:69]
	v_mfma_f32_16x16x32_f16 v[62:65], v[106:109], v[180:183], v[62:65]
	v_mfma_f32_16x16x32_f16 v[50:53], v[98:101], v[196:199], v[50:53]
	v_mfma_f32_16x16x32_f16 v[46:49], v[106:109], v[196:199], v[46:49]
	v_mfma_f32_16x16x32_f16 v[34:37], v[98:101], v[204:207], v[34:37]
	v_mfma_f32_16x16x32_f16 v[30:33], v[106:109], v[204:207], v[30:33]
	v_mfma_f32_16x16x32_f16 v[18:21], v[98:101], v[222:225], v[18:21]
	v_mfma_f32_16x16x32_f16 v[10:13], v[106:109], v[222:225], v[10:13]
	v_mfma_f32_16x16x32_f16 v[58:61], v[114:117], v[176:179], v[58:61]
	v_mfma_f32_16x16x32_f16 v[54:57], v[126:129], v[176:179], v[54:57]
	v_mfma_f32_16x16x32_f16 v[42:45], v[114:117], v[184:187], v[42:45]
	v_mfma_f32_16x16x32_f16 v[38:41], v[126:129], v[184:187], v[38:41]
	v_mfma_f32_16x16x32_f16 v[26:29], v[114:117], v[200:203], v[26:29]
	v_mfma_f32_16x16x32_f16 v[22:25], v[126:129], v[200:203], v[22:25]
	v_mfma_f32_16x16x32_f16 v[6:9], v[114:117], v[218:221], v[6:9]
	v_mfma_f32_16x16x32_f16 v[2:5], v[126:129], v[218:221], v[2:5]
	v_mfma_f32_16x16x32_f16 v[58:61], v[118:121], v[180:183], v[58:61]
	v_mfma_f32_16x16x32_f16 v[54:57], v[130:133], v[180:183], v[54:57]
	v_mfma_f32_16x16x32_f16 v[42:45], v[118:121], v[196:199], v[42:45]
	v_mfma_f32_16x16x32_f16 v[38:41], v[130:133], v[196:199], v[38:41]
	v_mfma_f32_16x16x32_f16 v[26:29], v[118:121], v[204:207], v[26:29]
	v_mfma_f32_16x16x32_f16 v[22:25], v[130:133], v[204:207], v[22:25]
	v_mfma_f32_16x16x32_f16 v[6:9], v[118:121], v[222:225], v[6:9]
	v_mfma_f32_16x16x32_f16 v[2:5], v[130:133], v[222:225], v[2:5]
	s_barrier
	s_add_i32 s12, 0, 0x18000
	s_add_i32 s13, 0, 0x1c000
	v_add_u32_e32 v106, s12, v191
	v_add_u32_e32 v130, s13, v191
	ds_read_b128 v[94:97], v106
	ds_read_b128 v[98:101], v106 offset:1024
	ds_read_b128 v[102:105], v106 offset:2048
	ds_read_b128 v[106:109], v106 offset:3072
	ds_read_b128 v[114:117], v130
	ds_read_b128 v[118:121], v130 offset:1024
	ds_read_b128 v[126:129], v130 offset:2048
	ds_read_b128 v[130:133], v130 offset:3072
	s_add_u32 s24, s24, 0x40000
	s_addc_u32 s25, s25, 0
	s_mov_b32 m0, s26
	v_lshl_add_u64 v[214:215], s[24:25], 0, v[170:171]
	ds_read_b128 v[176:179], v193 offset:32768
	ds_read_b128 v[180:183], v193 offset:33792
	ds_read_b128 v[184:187], v193 offset:34816
	ds_read_b128 v[196:199], v193 offset:35840
	ds_read_b128 v[200:203], v193 offset:36864
	ds_read_b128 v[204:207], v193 offset:37888
	ds_read_b128 v[218:221], v193 offset:38912
	ds_read_b128 v[222:225], v193 offset:39936
	global_load_lds_dwordx4 v[214:215], off
	v_lshl_add_u64 v[214:215], s[24:25], 0, v[166:167]
	s_mov_b32 m0, s27
	s_nop 0
	global_load_lds_dwordx4 v[214:215], off
	s_waitcnt vmcnt(8)
	s_waitcnt lgkmcnt(0)
	s_barrier
	v_mfma_f32_16x16x32_f16 v[162:165], v[94:97], v[176:179], v[162:165]
	v_mfma_f32_16x16x32_f16 v[158:161], v[102:105], v[176:179], v[158:161]
	v_mfma_f32_16x16x32_f16 v[146:149], v[94:97], v[184:187], v[146:149]
	v_mfma_f32_16x16x32_f16 v[142:145], v[102:105], v[184:187], v[142:145]
	v_mfma_f32_16x16x32_f16 v[122:125], v[94:97], v[200:203], v[122:125]
	v_mfma_f32_16x16x32_f16 v[110:113], v[102:105], v[200:203], v[110:113]
	v_mfma_f32_16x16x32_f16 v[82:85], v[94:97], v[218:221], v[82:85]
	v_mfma_f32_16x16x32_f16 v[78:81], v[102:105], v[218:221], v[78:81]
	v_mfma_f32_16x16x32_f16 v[162:165], v[98:101], v[180:183], v[162:165]
	v_mfma_f32_16x16x32_f16 v[158:161], v[106:109], v[180:183], v[158:161]
	v_mfma_f32_16x16x32_f16 v[146:149], v[98:101], v[196:199], v[146:149]
	v_mfma_f32_16x16x32_f16 v[142:145], v[106:109], v[196:199], v[142:145]
	v_mfma_f32_16x16x32_f16 v[122:125], v[98:101], v[204:207], v[122:125]
	v_mfma_f32_16x16x32_f16 v[110:113], v[106:109], v[204:207], v[110:113]
	v_mfma_f32_16x16x32_f16 v[82:85], v[98:101], v[222:225], v[82:85]
	v_mfma_f32_16x16x32_f16 v[78:81], v[106:109], v[222:225], v[78:81]
	v_mfma_f32_16x16x32_f16 v[154:157], v[114:117], v[176:179], v[154:157]
	v_mfma_f32_16x16x32_f16 v[150:153], v[126:129], v[176:179], v[150:153]
	v_mfma_f32_16x16x32_f16 v[138:141], v[114:117], v[184:187], v[138:141]
	v_mfma_f32_16x16x32_f16 v[134:137], v[126:129], v[184:187], v[134:137]
	v_mfma_f32_16x16x32_f16 v[90:93], v[114:117], v[200:203], v[90:93]
	v_mfma_f32_16x16x32_f16 v[86:89], v[126:129], v[200:203], v[86:89]
	v_mfma_f32_16x16x32_f16 v[74:77], v[114:117], v[218:221], v[74:77]
	v_mfma_f32_16x16x32_f16 v[70:73], v[126:129], v[218:221], v[70:73]
	v_mfma_f32_16x16x32_f16 v[154:157], v[118:121], v[180:183], v[154:157]
	v_mfma_f32_16x16x32_f16 v[150:153], v[130:133], v[180:183], v[150:153]
	v_mfma_f32_16x16x32_f16 v[138:141], v[118:121], v[196:199], v[138:141]
	v_mfma_f32_16x16x32_f16 v[134:137], v[130:133], v[196:199], v[134:137]
	v_mfma_f32_16x16x32_f16 v[90:93], v[118:121], v[204:207], v[90:93]
	v_mfma_f32_16x16x32_f16 v[86:89], v[130:133], v[204:207], v[86:89]
	v_mfma_f32_16x16x32_f16 v[74:77], v[118:121], v[222:225], v[74:77]
	v_mfma_f32_16x16x32_f16 v[70:73], v[130:133], v[222:225], v[70:73]
	s_barrier
; #define PG8_STAGE(bufoff, gbase, voff) do { _Pragma("unroll") for (int _i = 0; _i < 2; ++_i) \
;         __builtin_amdgcn_global_load_lds((const unsigned*)((const char*)(gbase) + (voff)[_i]), (PG8_LAS unsigned*)(lds + (bufoff) + ldsw + _i * 8192), 16, 0, 0); } while (0)
; #define PG8_LDA(dst, b, h) do { _Pragma("unroll") for (int m = 0; m < 4; ++m) _Pragma("unroll") for (int k = 0; k < 2; ++k) dst[m][k] = *(const PG8_LAS bf16x8*)(lds + PG8_SA(b, h) + aoff + m * 2048 + k * 1024); } while (0)
; #define PG8_MMA(ai, bj, At, Bt) do { __builtin_amdgcn_s_setprio(1); _Pragma("unroll") for (int m = 0; m < 4; ++m) _Pragma("unroll") for (int n = 0; n < 2; ++n) _Pragma("unroll") for (int k = 0; k < 2; ++k) \
;         acc[ai][bj][m][n] = __builtin_amdgcn_mfma_f32_16x16x32_f16(Bt[n][k], At[m][k], acc[ai][bj][m][n], 0, 0, 0); __builtin_amdgcn_s_setprio(0); } while (0)
; #define PG8_WAIT_V(n) asm volatile("s_waitcnt vmcnt(" #n ")" ::: "memory")
; #define PG8_WAIT_L(n) asm volatile("s_waitcnt lgkmcnt(" #n ")" ::: "memory")
; #define PG8_BAR __builtin_amdgcn_s_barrier()
; #define PG8_SCHED __builtin_amdgcn_sched_barrier(0)
; template <class Epi, class Sched, bool ALIGN_EPI = false, bool SP2 = false>
; __device__ __forceinline__ void gemm_phase(PG8_LAS unsigned char* lds, const Gemm g, const Sched& S, const Epi& E) {
;     ...
;             PG8_LDA(At, 1, 1); PG8_STAGE(PG8_SB(1, 0), b3, voffB); PG8_STAGE(PG8_SB(1, 1), b3 + hstep, voffB); PG8_STAGE(PG8_SA(1, 0), a3, voffA);
;             PG8_WAIT_V(8); PG8_WAIT_L(0); PG8_BAR; PG8_MMA(1, 0, At, B0); PG8_MMA(1, 1, At, B1); PG8_BAR; PG8_SCHED;
	s_add_i32 s12, s12, s5
	v_lshl_add_u64 v[188:189], v[188:189], 0, s[34:35]
	s_mov_b32 m0, s12
	ds_read_b128 v[176:179], v193 offset:49152
	ds_read_b128 v[180:183], v193 offset:50176
	ds_read_b128 v[184:187], v193 offset:51200
	ds_read_b128 v[196:199], v193 offset:52224
	ds_read_b128 v[200:203], v193 offset:53248
	ds_read_b128 v[204:207], v193 offset:54272
	ds_read_b128 v[218:221], v193 offset:55296
	ds_read_b128 v[222:225], v193 offset:56320
	global_load_lds_dwordx4 v[188:189], off
	s_add_i32 m0, s12, 0x2000
	s_add_u32 s22, s22, 0x40080
	v_lshl_add_u64 v[188:189], v[208:209], 0, s[34:35]
	s_addc_u32 s23, s23, 0
	s_add_i32 s12, s13, s5
	global_load_lds_dwordx4 v[188:189], off
	v_lshl_add_u64 v[188:189], s[22:23], 0, v[168:169]
	s_mov_b32 m0, s12
	s_nop 0
	global_load_lds_dwordx4 v[188:189], off
	v_lshl_add_u64 v[188:189], s[22:23], 0, v[14:15]
	s_add_i32 m0, s12, 0x2000
	s_nop 0
	global_load_lds_dwordx4 v[188:189], off
	v_lshl_add_u64 v[188:189], v[210:211], 0, s[34:35]
	s_mov_b32 m0, s49
	s_nop 0
	global_load_lds_dwordx4 v[188:189], off
	v_lshl_add_u64 v[188:189], v[212:213], 0, s[34:35]
	s_mov_b32 m0, s58
	s_nop 0
	global_load_lds_dwordx4 v[188:189], off
	s_waitcnt vmcnt(8)
	s_waitcnt lgkmcnt(0)
	s_barrier
	v_mfma_f32_16x16x32_f16 v[66:69], v[94:97], v[176:179], v[66:69]
	v_mfma_f32_16x16x32_f16 v[62:65], v[102:105], v[176:179], v[62:65]
	v_mfma_f32_16x16x32_f16 v[50:53], v[94:97], v[184:187], v[50:53]
	v_mfma_f32_16x16x32_f16 v[46:49], v[102:105], v[184:187], v[46:49]
	v_mfma_f32_16x16x32_f16 v[34:37], v[94:97], v[200:203], v[34:37]
	v_mfma_f32_16x16x32_f16 v[30:33], v[102:105], v[200:203], v[30:33]
	v_mfma_f32_16x16x32_f16 v[18:21], v[94:97], v[218:221], v[18:21]
	v_mfma_f32_16x16x32_f16 v[10:13], v[102:105], v[218:221], v[10:13]
	v_mfma_f32_16x16x32_f16 v[66:69], v[98:101], v[180:183], v[66:69]
	v_mfma_f32_16x16x32_f16 v[62:65], v[106:109], v[180:183], v[62:65]
	v_mfma_f32_16x16x32_f16 v[50:53], v[98:101], v[196:199], v[50:53]
	v_mfma_f32_16x16x32_f16 v[46:49], v[106:109], v[196:199], v[46:49]
	v_mfma_f32_16x16x32_f16 v[34:37], v[98:101], v[204:207], v[34:37]
	v_mfma_f32_16x16x32_f16 v[30:33], v[106:109], v[204:207], v[30:33]
	v_mfma_f32_16x16x32_f16 v[18:21], v[98:101], v[222:225], v[18:21]
	v_mfma_f32_16x16x32_f16 v[10:13], v[106:109], v[222:225], v[10:13]
	v_mfma_f32_16x16x32_f16 v[58:61], v[114:117], v[176:179], v[58:61]
	v_mfma_f32_16x16x32_f16 v[54:57], v[126:129], v[176:179], v[54:57]
	v_mfma_f32_16x16x32_f16 v[42:45], v[114:117], v[184:187], v[42:45]
	v_mfma_f32_16x16x32_f16 v[38:41], v[126:129], v[184:187], v[38:41]
	v_mfma_f32_16x16x32_f16 v[26:29], v[114:117], v[200:203], v[26:29]
	v_mfma_f32_16x16x32_f16 v[22:25], v[126:129], v[200:203], v[22:25]
	v_mfma_f32_16x16x32_f16 v[6:9], v[114:117], v[218:221], v[6:9]
	v_mfma_f32_16x16x32_f16 v[2:5], v[126:129], v[218:221], v[2:5]
	v_mfma_f32_16x16x32_f16 v[58:61], v[118:121], v[180:183], v[58:61]
	v_mfma_f32_16x16x32_f16 v[54:57], v[130:133], v[180:183], v[54:57]
	v_mfma_f32_16x16x32_f16 v[42:45], v[118:121], v[196:199], v[42:45]
	v_mfma_f32_16x16x32_f16 v[38:41], v[130:133], v[196:199], v[38:41]
	v_mfma_f32_16x16x32_f16 v[26:29], v[118:121], v[204:207], v[26:29]
	v_mfma_f32_16x16x32_f16 v[22:25], v[130:133], v[204:207], v[22:25]
	v_mfma_f32_16x16x32_f16 v[6:9], v[118:121], v[222:225], v[6:9]
	v_mfma_f32_16x16x32_f16 v[2:5], v[130:133], v[222:225], v[2:5]
	s_barrier
	s_add_i32 s83, s83, 2
	s_add_u32 s50, s50, 0x100
	s_addc_u32 s51, s51, 0
	s_add_u32 s77, s77, 0x100
	s_addc_u32 s82, s82, 0
	s_cmp_gt_u32 s83, 13
	s_cbranch_scc0 .LBB0_185
	s_and_b64 vcc, exec, s[14:15]
	s_cbranch_vccz .LBB0_188
	s_barrier

; #define PG8_STAGE(bufoff, gbase, voff) do { _Pragma("unroll") for (int _i = 0; _i < 2; ++_i) \
;         __builtin_amdgcn_global_load_lds((const unsigned*)((const char*)(gbase) + (voff)[_i]), (PG8_LAS unsigned*)(lds + (bufoff) + ldsw + _i * 8192), 16, 0, 0); } while (0)
; #define PG8_WAIT_V(n) asm volatile("s_waitcnt vmcnt(" #n ")" ::: "memory")
; #define PG8_BAR __builtin_amdgcn_s_barrier()
; template <class Epi, class Sched, bool ALIGN_EPI = false, bool SP2 = false>
; __device__ __forceinline__ void gemm_phase(PG8_LAS unsigned char* lds, const Gemm g, const Sched& S, const Epi& E) {
;     ...
;     for (int i = 0; i < 2; ++i) { int R, C; stage_rc(tid * 16 + i * 8192, R, C); const int Rb = Epi::PERM ? ((R & ~31) + perm32(R & 31)) : R;
;         voffA[i] = (unsigned)(R * K + C) * 2u; voffB[i] = (unsigned)(Rb * K + C) * 2u; }
;     const size_t kstep = (size_t)(BK * 2);
;     const size_t hstep = (size_t)HALF * K * 2;
;     const size_t tstep = 2 * hstep;
;     const unsigned ldsw = (unsigned)wid * 1024u;
;     const int aoff = lds_byte(wr * 64 + fr, fq * 8), boff = lds_byte(wc * 32 + fr, fq * 8);
;     ...
;     if constexpr (SP2) {
;         PG8_STAGE(PG8_SB(0, 0), cB, voffB); PG8_STAGE(PG8_SB(0, 1), cB + hstep, voffB); PG8_STAGE(PG8_SA(0, 0), cA, voffA); PG8_STAGE(PG8_SA(0, 1), cA + hstep, voffA);
;         if (wr == 1) PG8_BAR;
;         PG8_WAIT_V(2); PG8_BAR;
;         PG8_STAGE(PG8_SB(1, 0), cB + kstep, voffB); PG8_STAGE(PG8_SA(1, 0), cA + kstep, voffA); PG8_STAGE(PG8_SB(1, 1), cB + hstep + kstep, voffB);
;         PG8_WAIT_V(6); PG8_BAR;
.LBB0_263:
	v_mov_b32_e32 v137, v0
	v_lshl_add_u64 v[10:11], s[22:23], 0, v[136:137]
	s_waitcnt vmcnt(0)
	v_mov_b32_e32 v15, v0
	v_readlane_b32 s24, v254, 49
	s_lshl_b32 s14, s14, 5
	v_lshl_add_u64 v[12:13], s[22:23], 0, v[14:15]
	v_mov_b32_e32 v139, v0
	v_readlane_b32 s25, v254, 50
	s_and_b32 s28, s14, 0x60
	s_add_i32 m0, s10, 0x18000
	v_lshl_add_u64 v[10:11], v[10:11], 0, s[34:35]
	v_lshl_add_u64 v[18:19], s[24:25], 0, v[138:139]
	v_mov_b32_e32 v135, v0
	s_lshl_b32 s27, s15, 6
	s_lshl_b32 s13, s15, 13
	s_lshl_b32 s16, s28, 7
	s_waitcnt vmcnt(2)
	s_barrier
	global_load_lds_dwordx4 v[10:11], off
	v_lshl_add_u64 v[10:11], v[12:13], 0, s[34:35]
	s_add_i32 m0, s10, 0x1a000
	s_add_i32 s29, s10, 0x8000
	s_add_i32 s33, s10, 0xa000
	v_lshl_add_u64 v[20:21], s[24:25], 0, v[134:135]
	global_load_lds_dwordx4 v[10:11], off
	v_lshl_add_u64 v[10:11], v[18:19], 0, s[34:35]
	s_mov_b32 m0, s29
	s_add_u32 s14, s22, 0x40080
	global_load_lds_dwordx4 v[10:11], off
	v_lshl_add_u64 v[10:11], v[20:21], 0, s[34:35]
	s_mov_b32 m0, s33
	s_addc_u32 s15, s23, 0
	global_load_lds_dwordx4 v[10:11], off
	s_add_i32 m0, s10, 0x1c000
	v_lshl_add_u64 v[10:11], s[14:15], 0, v[136:137]
	global_load_lds_dwordx4 v[10:11], off
	v_lshl_add_u64 v[10:11], s[14:15], 0, v[14:15]
	s_add_i32 m0, s10, 0x1e000
	v_lshrrev_b32_e32 v9, 1, v2
	global_load_lds_dwordx4 v[10:11], off
	v_and_b32_e32 v17, 24, v9
	v_and_b32_e32 v1, 15, v2
	v_lshlrev_b32_e32 v9, 1, v17
	v_lshlrev_b32_e32 v2, 2, v2
	v_lshl_or_b32 v9, v1, 6, v9
	v_and_b32_e32 v2, 32, v2
	v_bitop3_b32 v10, v9, s13, v2 bitop3:0xde
	v_bitop3_b32 v154, v9, s16, v2 bitop3:0xde
	v_lshlrev_b32_e32 v2, 14, v7
	v_and_b32_e32 v2, 0xffff8000, v2
	v_lshl_add_u32 v2, v6, 11, v2
	v_and_b32_e32 v6, 1, v7
	v_lshl_or_b32 v2, v6, 6, v2
	v_lshl_add_u32 v140, v8, 1, v2
	v_lshlrev_b32_e32 v2, 14, v3
	v_and_b32_e32 v2, 0xffff8000, v2
	s_waitcnt vmcnt(6)
	v_lshl_add_u32 v2, v4, 11, v2
	v_and_b32_e32 v3, 1, v3
	s_cmpk_lt_u32 s12, 0x100
	v_lshl_or_b32 v2, v3, 6, v2
	v_readlane_b32 s12, v254, 39
	s_cselect_b64 s[14:15], -1, 0
	v_mov_b32_e32 v141, v0
	v_lshl_add_u32 v142, v5, 1, v2
	v_mov_b32_e32 v143, v0
	s_mov_b32 s49, 0
	v_add_u32_e32 v155, 0, v10
	v_readlane_b32 s58, v254, 29
	s_mov_b32 s71, s12
	s_barrier
	v_readlane_b32 s13, v254, 40
	s_mov_b32 s32, 1
	s_branch .LBB0_266

; #define PG8_BAR __builtin_amdgcn_s_barrier()
; template <class Epi, class Sched, bool ALIGN_EPI = false, bool SP2 = false>
; __device__ __forceinline__ void gemm_phase(PG8_LAS unsigned char* lds, const Gemm g, const Sched& S, const Epi& E) {
;     ...
;         if (!has_next) break;
; #pragma unroll
;         for (int a = 0; a < 2; ++a)
; #pragma unroll
;             for (int b = 0; b < 2; ++b)
; #pragma unroll
;                 for (int m = 0; m < 4; ++m)
; #pragma unroll
;                     for (int n = 0; n < 2; ++n) acc[a][b][m][n] = (f32x4){0.f, 0.f, 0.f, 0.f};
;         cur = nxt; cA = nA; cB = nB; ++ui;
;         if constexpr (ALIGN_EPI) { if (wr == 1) PG8_BAR; }
.LBB0_265:
	s_mov_b32 s32, -2
	s_andn2_b64 vcc, exec, s[22:23]
	s_mov_b32 s58, s16
	s_mov_b32 s71, s38
	s_mov_b64 s[22:23], s[42:43]
	s_mov_b64 s[24:25], s[40:41]
	s_cbranch_vccz .LBB0_339

; #define PG8_STAGE(bufoff, gbase, voff) do { _Pragma("unroll") for (int _i = 0; _i < 2; ++_i) \
;         __builtin_amdgcn_global_load_lds((const unsigned*)((const char*)(gbase) + (voff)[_i]), (PG8_LAS unsigned*)(lds + (bufoff) + ldsw + _i * 8192), 16, 0, 0); } while (0)
; #define PG8_LDA(dst, b, h) do { _Pragma("unroll") for (int m = 0; m < 4; ++m) _Pragma("unroll") for (int k = 0; k < 2; ++k) dst[m][k] = *(const PG8_LAS bf16x8*)(lds + PG8_SA(b, h) + aoff + m * 2048 + k * 1024); } while (0)
; #define PG8_LDB(dst, b, h) do { _Pragma("unroll") for (int n = 0; n < 2; ++n) _Pragma("unroll") for (int k = 0; k < 2; ++k) dst[n][k] = *(const PG8_LAS bf16x8*)(lds + PG8_SB(b, h) + boff + n * 2048 + k * 1024); } while (0)
; #define PG8_SCHED __builtin_amdgcn_sched_barrier(0)
; template <class Epi, class Sched, bool ALIGN_EPI = false, bool SP2 = false>
; __device__ __forceinline__ void gemm_phase(PG8_LAS unsigned char* lds, const Gemm g, const Sched& S, const Epi& E) {
;     ...
;             const bool last = (t == nt - 2);
;             const char* a1 = cA + (size_t)(t + 1) * kstep;
;             const char* a2 = last ? nA : cA + (size_t)(t + 2) * kstep; const char* b2 = last ? nB : cB + (size_t)(t + 2) * kstep;
;             const char* a3 = a2 + kstep; const char* b3 = b2 + kstep;
;             if (last && has_next) S.a_ready(nxt);
;             if constexpr (SP2) {
;             PG8_LDB(B0, 0, 0); PG8_LDB(B1, 0, 1); PG8_SCHED; PG8_LDA(At, 0, 0); PG8_STAGE(PG8_SA(1, 1), a1 + hstep, voffA);
.LBB0_269:
	s_add_u32 s12, s50, 0xfffc0080
	s_addc_u32 s13, s51, -1
	s_add_i32 s83, 0, 0x10000
	s_cmp_eq_u32 s82, 12
	s_cselect_b32 s25, s39, s13
	s_cselect_b32 s24, s72, s12
	v_add_u32_e32 v152, s83, v154
	s_cselect_b32 s23, s17, s77
	s_cselect_b32 s22, s73, s76
	s_add_i32 s12, 0, 0x14000
	ds_read_b128 v[144:147], v152
	ds_read_b128 v[148:151], v152 offset:1024
	ds_read_b128 v[156:159], v152 offset:2048
	ds_read_b128 v[160:163], v152 offset:3072
	v_add_u32_e32 v152, s12, v154
	ds_read_b128 v[164:167], v152
	ds_read_b128 v[168:171], v152 offset:1024
	ds_read_b128 v[172:175], v152 offset:2048
	ds_read_b128 v[176:179], v152 offset:3072
	v_lshl_add_u64 v[152:153], s[50:51], 0, v[140:141]
	s_add_i32 m0, s10, 0xc000
	ds_read_b128 v[180:183], v155
	ds_read_b128 v[184:187], v155 offset:1024
	ds_read_b128 v[188:191], v155 offset:2048
	ds_read_b128 v[192:195], v155 offset:3072
	ds_read_b128 v[196:199], v155 offset:4096
	ds_read_b128 v[200:203], v155 offset:5120
	ds_read_b128 v[204:207], v155 offset:6144
	ds_read_b128 v[218:221], v155 offset:7168
	global_load_lds_dwordx4 v[152:153], off
	v_lshl_add_u64 v[152:153], s[50:51], 0, v[142:143]
	s_add_i32 m0, s10, 0xe000
	s_nop 0
	global_load_lds_dwordx4 v[152:153], off
	s_cmp_lg_u32 s12, s32
	s_cbranch_scc1 .Lfw8_269_0
	s_waitcnt vmcnt(23)
	s_branch .Lfwd_269_0

; #define PG8_STAGE(bufoff, gbase, voff) do { _Pragma("unroll") for (int _i = 0; _i < 2; ++_i) \
;         __builtin_amdgcn_global_load_lds((const unsigned*)((const char*)(gbase) + (voff)[_i]), (PG8_LAS unsigned*)(lds + (bufoff) + ldsw + _i * 8192), 16, 0, 0); } while (0)
; #define PG8_LDA(dst, b, h) do { _Pragma("unroll") for (int m = 0; m < 4; ++m) _Pragma("unroll") for (int k = 0; k < 2; ++k) dst[m][k] = *(const PG8_LAS bf16x8*)(lds + PG8_SA(b, h) + aoff + m * 2048 + k * 1024); } while (0)
; #define PG8_MMA(ai, bj, At, Bt) do { __builtin_amdgcn_s_setprio(1); _Pragma("unroll") for (int m = 0; m < 4; ++m) _Pragma("unroll") for (int n = 0; n < 2; ++n) _Pragma("unroll") for (int k = 0; k < 2; ++k) \
;         acc[ai][bj][m][n] = __builtin_amdgcn_mfma_f32_16x16x32_f16(Bt[n][k], At[m][k], acc[ai][bj][m][n], 0, 0, 0); __builtin_amdgcn_s_setprio(0); } while (0)
; #define PG8_WAIT_V(n) asm volatile("s_waitcnt vmcnt(" #n ")" ::: "memory")
; #define PG8_WAIT_L(n) asm volatile("s_waitcnt lgkmcnt(" #n ")" ::: "memory")
; #define PG8_BAR __builtin_amdgcn_s_barrier()
; #define PG8_SCHED __builtin_amdgcn_sched_barrier(0)
; template <class Epi, class Sched, bool ALIGN_EPI = false, bool SP2 = false>
; __device__ __forceinline__ void gemm_phase(PG8_LAS unsigned char* lds, const Gemm g, const Sched& S, const Epi& E) {
;     ...
;             PG8_WAIT_V(8); PG8_WAIT_L(0); PG8_BAR; PG8_MMA(0, 0, At, B0); PG8_MMA(0, 1, At, B1); PG8_BAR; PG8_SCHED;
;             PG8_LDA(At, 0, 1); PG8_STAGE(PG8_SB(0, 0), b2, voffB); PG8_STAGE(PG8_SB(0, 1), b2 + hstep, voffB); PG8_STAGE(PG8_SA(0, 0), a2, voffA);
.Lfwd_269_0:
	s_waitcnt lgkmcnt(0)
	s_barrier
	v_mfma_f32_16x16x32_f16 v[130:133], v[144:147], v[180:183], v[130:133]
	v_mfma_f32_16x16x32_f16 v[126:129], v[156:159], v[180:183], v[126:129]
	v_mfma_f32_16x16x32_f16 v[114:117], v[144:147], v[188:191], v[114:117]
	v_mfma_f32_16x16x32_f16 v[110:113], v[156:159], v[188:191], v[110:113]
	v_mfma_f32_16x16x32_f16 v[98:101], v[144:147], v[196:199], v[98:101]
	v_mfma_f32_16x16x32_f16 v[94:97], v[156:159], v[196:199], v[94:97]
	v_mfma_f32_16x16x32_f16 v[82:85], v[144:147], v[204:207], v[82:85]
	v_mfma_f32_16x16x32_f16 v[78:81], v[156:159], v[204:207], v[78:81]
	v_mfma_f32_16x16x32_f16 v[130:133], v[148:151], v[184:187], v[130:133]
	v_mfma_f32_16x16x32_f16 v[126:129], v[160:163], v[184:187], v[126:129]
	v_mfma_f32_16x16x32_f16 v[114:117], v[148:151], v[192:195], v[114:117]
	v_mfma_f32_16x16x32_f16 v[110:113], v[160:163], v[192:195], v[110:113]
	v_mfma_f32_16x16x32_f16 v[98:101], v[148:151], v[200:203], v[98:101]
	v_mfma_f32_16x16x32_f16 v[94:97], v[160:163], v[200:203], v[94:97]
	v_mfma_f32_16x16x32_f16 v[82:85], v[148:151], v[218:221], v[82:85]
	v_mfma_f32_16x16x32_f16 v[78:81], v[160:163], v[218:221], v[78:81]
	v_mfma_f32_16x16x32_f16 v[122:125], v[164:167], v[180:183], v[122:125]
	v_mfma_f32_16x16x32_f16 v[118:121], v[172:175], v[180:183], v[118:121]
	v_mfma_f32_16x16x32_f16 v[106:109], v[164:167], v[188:191], v[106:109]
	v_mfma_f32_16x16x32_f16 v[102:105], v[172:175], v[188:191], v[102:105]
	v_mfma_f32_16x16x32_f16 v[90:93], v[164:167], v[196:199], v[90:93]
	v_mfma_f32_16x16x32_f16 v[86:89], v[172:175], v[196:199], v[86:89]
	v_mfma_f32_16x16x32_f16 v[74:77], v[164:167], v[204:207], v[74:77]
	v_mfma_f32_16x16x32_f16 v[70:73], v[172:175], v[204:207], v[70:73]
	v_mfma_f32_16x16x32_f16 v[122:125], v[168:171], v[184:187], v[122:125]
	v_mfma_f32_16x16x32_f16 v[118:121], v[176:179], v[184:187], v[118:121]
	v_mfma_f32_16x16x32_f16 v[106:109], v[168:171], v[192:195], v[106:109]
	v_mfma_f32_16x16x32_f16 v[102:105], v[176:179], v[192:195], v[102:105]
	v_mfma_f32_16x16x32_f16 v[90:93], v[168:171], v[200:203], v[90:93]
	v_mfma_f32_16x16x32_f16 v[86:89], v[176:179], v[200:203], v[86:89]
	v_mfma_f32_16x16x32_f16 v[74:77], v[168:171], v[218:221], v[74:77]
	v_mfma_f32_16x16x32_f16 v[70:73], v[176:179], v[218:221], v[70:73]
	s_barrier
	s_add_i32 s13, s83, s5
	v_lshl_add_u64 v[152:153], s[22:23], 0, v[136:137]
	s_mov_b32 m0, s13
	ds_read_b128 v[180:183], v155 offset:16384
	ds_read_b128 v[184:187], v155 offset:17408
	ds_read_b128 v[188:191], v155 offset:18432
	ds_read_b128 v[192:195], v155 offset:19456
	ds_read_b128 v[196:199], v155 offset:20480
	ds_read_b128 v[200:203], v155 offset:21504
	ds_read_b128 v[204:207], v155 offset:22528
	ds_read_b128 v[218:221], v155 offset:23552
	global_load_lds_dwordx4 v[152:153], off
	s_add_i32 m0, s13, 0x2000
	s_add_u32 vcc_lo, s22, 0x40000
	v_lshl_add_u64 v[208:209], s[22:23], 0, v[14:15]
	s_addc_u32 vcc_hi, s23, 0
	s_add_i32 s12, s12, s5
	global_load_lds_dwordx4 v[208:209], off
	v_lshl_add_u64 v[210:211], vcc, 0, v[136:137]
	s_mov_b32 m0, s12
	v_lshl_add_u64 v[212:213], s[24:25], 0, v[134:135]
	global_load_lds_dwordx4 v[210:211], off
	v_lshl_add_u64 v[210:211], vcc, 0, v[14:15]
	s_add_i32 m0, s12, 0x2000
	s_nop 0
	global_load_lds_dwordx4 v[210:211], off
	v_lshl_add_u64 v[210:211], s[24:25], 0, v[138:139]
	s_mov_b32 m0, s10
	s_nop 0
	global_load_lds_dwordx4 v[210:211], off
	s_mov_b32 m0, s11
	s_nop 0
	global_load_lds_dwordx4 v[212:213], off
	s_cmp_lg_u32 s12, s32
	s_cbranch_scc1 .Lfw8_269_1
	s_waitcnt vmcnt(23)
	s_branch .Lfwd_269_1

; #define PG8_STAGE(bufoff, gbase, voff) do { _Pragma("unroll") for (int _i = 0; _i < 2; ++_i) \
;         __builtin_amdgcn_global_load_lds((const unsigned*)((const char*)(gbase) + (voff)[_i]), (PG8_LAS unsigned*)(lds + (bufoff) + ldsw + _i * 8192), 16, 0, 0); } while (0)
; #define PG8_LDA(dst, b, h) do { _Pragma("unroll") for (int m = 0; m < 4; ++m) _Pragma("unroll") for (int k = 0; k < 2; ++k) dst[m][k] = *(const PG8_LAS bf16x8*)(lds + PG8_SA(b, h) + aoff + m * 2048 + k * 1024); } while (0)
; #define PG8_LDB(dst, b, h) do { _Pragma("unroll") for (int n = 0; n < 2; ++n) _Pragma("unroll") for (int k = 0; k < 2; ++k) dst[n][k] = *(const PG8_LAS bf16x8*)(lds + PG8_SB(b, h) + boff + n * 2048 + k * 1024); } while (0)
; #define PG8_MMA(ai, bj, At, Bt) do { __builtin_amdgcn_s_setprio(1); _Pragma("unroll") for (int m = 0; m < 4; ++m) _Pragma("unroll") for (int n = 0; n < 2; ++n) _Pragma("unroll") for (int k = 0; k < 2; ++k) \
;         acc[ai][bj][m][n] = __builtin_amdgcn_mfma_f32_16x16x32_f16(Bt[n][k], At[m][k], acc[ai][bj][m][n], 0, 0, 0); __builtin_amdgcn_s_setprio(0); } while (0)
; #define PG8_WAIT_V(n) asm volatile("s_waitcnt vmcnt(" #n ")" ::: "memory")
; #define PG8_WAIT_L(n) asm volatile("s_waitcnt lgkmcnt(" #n ")" ::: "memory")
; #define PG8_BAR __builtin_amdgcn_s_barrier()
; #define PG8_SCHED __builtin_amdgcn_sched_barrier(0)
; template <class Epi, class Sched, bool ALIGN_EPI = false, bool SP2 = false>
; __device__ __forceinline__ void gemm_phase(PG8_LAS unsigned char* lds, const Gemm g, const Sched& S, const Epi& E) {
;     ...
;             PG8_WAIT_V(8); PG8_WAIT_L(0); PG8_BAR; PG8_MMA(1, 0, At, B0); PG8_MMA(1, 1, At, B1); PG8_BAR; PG8_SCHED;
;             PG8_LDB(B0, 1, 0); PG8_LDB(B1, 1, 1); PG8_SCHED; PG8_LDA(At, 1, 0); PG8_STAGE(PG8_SA(0, 1), a2 + hstep, voffA);
;             PG8_WAIT_V(8); PG8_WAIT_L(0); PG8_BAR; PG8_MMA(0, 0, At, B0); PG8_MMA(0, 1, At, B1); PG8_BAR; PG8_SCHED;
.Lfwd_269_1:
	s_waitcnt lgkmcnt(0)
	s_barrier
	v_mfma_f32_16x16x32_f16 v[66:69], v[144:147], v[180:183], v[66:69]
	v_mfma_f32_16x16x32_f16 v[62:65], v[156:159], v[180:183], v[62:65]
	v_mfma_f32_16x16x32_f16 v[50:53], v[144:147], v[188:191], v[50:53]
	v_mfma_f32_16x16x32_f16 v[46:49], v[156:159], v[188:191], v[46:49]
	v_mfma_f32_16x16x32_f16 v[34:37], v[144:147], v[196:199], v[34:37]
	v_mfma_f32_16x16x32_f16 v[30:33], v[156:159], v[196:199], v[30:33]
	v_mfma_f32_16x16x32_f16 v[18:21], v[144:147], v[204:207], v[18:21]
	v_mfma_f32_16x16x32_f16 v[10:13], v[156:159], v[204:207], v[10:13]
	v_mfma_f32_16x16x32_f16 v[66:69], v[148:151], v[184:187], v[66:69]
	v_mfma_f32_16x16x32_f16 v[62:65], v[160:163], v[184:187], v[62:65]
	v_mfma_f32_16x16x32_f16 v[50:53], v[148:151], v[192:195], v[50:53]
	v_mfma_f32_16x16x32_f16 v[46:49], v[160:163], v[192:195], v[46:49]
	v_mfma_f32_16x16x32_f16 v[34:37], v[148:151], v[200:203], v[34:37]
	v_mfma_f32_16x16x32_f16 v[30:33], v[160:163], v[200:203], v[30:33]
	v_mfma_f32_16x16x32_f16 v[18:21], v[148:151], v[218:221], v[18:21]
	v_mfma_f32_16x16x32_f16 v[10:13], v[160:163], v[218:221], v[10:13]
	v_mfma_f32_16x16x32_f16 v[58:61], v[164:167], v[180:183], v[58:61]
	v_mfma_f32_16x16x32_f16 v[54:57], v[172:175], v[180:183], v[54:57]
	v_mfma_f32_16x16x32_f16 v[42:45], v[164:167], v[188:191], v[42:45]
	v_mfma_f32_16x16x32_f16 v[38:41], v[172:175], v[188:191], v[38:41]
	v_mfma_f32_16x16x32_f16 v[26:29], v[164:167], v[196:199], v[26:29]
	v_mfma_f32_16x16x32_f16 v[22:25], v[172:175], v[196:199], v[22:25]
	v_mfma_f32_16x16x32_f16 v[6:9], v[164:167], v[204:207], v[6:9]
	v_mfma_f32_16x16x32_f16 v[2:5], v[172:175], v[204:207], v[2:5]
	v_mfma_f32_16x16x32_f16 v[58:61], v[168:171], v[184:187], v[58:61]
	v_mfma_f32_16x16x32_f16 v[54:57], v[176:179], v[184:187], v[54:57]
	v_mfma_f32_16x16x32_f16 v[42:45], v[168:171], v[192:195], v[42:45]
	v_mfma_f32_16x16x32_f16 v[38:41], v[176:179], v[192:195], v[38:41]
	v_mfma_f32_16x16x32_f16 v[26:29], v[168:171], v[200:203], v[26:29]
	v_mfma_f32_16x16x32_f16 v[22:25], v[176:179], v[200:203], v[22:25]
	v_mfma_f32_16x16x32_f16 v[6:9], v[168:171], v[218:221], v[6:9]
	v_mfma_f32_16x16x32_f16 v[2:5], v[176:179], v[218:221], v[2:5]
	s_barrier
	s_add_i32 s12, 0, 0x18000
	s_add_i32 s13, 0, 0x1c000
	v_add_u32_e32 v160, s12, v154
	v_add_u32_e32 v176, s13, v154
	ds_read_b128 v[144:147], v160
	ds_read_b128 v[148:151], v160 offset:1024
	ds_read_b128 v[156:159], v160 offset:2048
	ds_read_b128 v[160:163], v160 offset:3072
	ds_read_b128 v[164:167], v176
	ds_read_b128 v[168:171], v176 offset:1024
	ds_read_b128 v[172:175], v176 offset:2048
	ds_read_b128 v[176:179], v176 offset:3072
	s_add_u32 s24, s24, 0x40000
	s_addc_u32 s25, s25, 0
	s_mov_b32 m0, s20
	v_lshl_add_u64 v[214:215], s[24:25], 0, v[138:139]
	ds_read_b128 v[180:183], v155 offset:32768
	ds_read_b128 v[184:187], v155 offset:33792
	ds_read_b128 v[188:191], v155 offset:34816
	ds_read_b128 v[192:195], v155 offset:35840
	ds_read_b128 v[196:199], v155 offset:36864
	ds_read_b128 v[200:203], v155 offset:37888
	ds_read_b128 v[204:207], v155 offset:38912
	ds_read_b128 v[218:221], v155 offset:39936
	global_load_lds_dwordx4 v[214:215], off
	v_lshl_add_u64 v[214:215], s[24:25], 0, v[134:135]
	s_mov_b32 m0, s26
	s_nop 0
	global_load_lds_dwordx4 v[214:215], off
	s_waitcnt vmcnt(8)
	s_waitcnt lgkmcnt(0)
	s_barrier
	v_mfma_f32_16x16x32_f16 v[130:133], v[144:147], v[180:183], v[130:133]
	v_mfma_f32_16x16x32_f16 v[126:129], v[156:159], v[180:183], v[126:129]
	v_mfma_f32_16x16x32_f16 v[114:117], v[144:147], v[188:191], v[114:117]
	v_mfma_f32_16x16x32_f16 v[110:113], v[156:159], v[188:191], v[110:113]
	v_mfma_f32_16x16x32_f16 v[98:101], v[144:147], v[196:199], v[98:101]
	v_mfma_f32_16x16x32_f16 v[94:97], v[156:159], v[196:199], v[94:97]
	v_mfma_f32_16x16x32_f16 v[82:85], v[144:147], v[204:207], v[82:85]
	v_mfma_f32_16x16x32_f16 v[78:81], v[156:159], v[204:207], v[78:81]
	v_mfma_f32_16x16x32_f16 v[130:133], v[148:151], v[184:187], v[130:133]
	v_mfma_f32_16x16x32_f16 v[126:129], v[160:163], v[184:187], v[126:129]
	v_mfma_f32_16x16x32_f16 v[114:117], v[148:151], v[192:195], v[114:117]
	v_mfma_f32_16x16x32_f16 v[110:113], v[160:163], v[192:195], v[110:113]
	v_mfma_f32_16x16x32_f16 v[98:101], v[148:151], v[200:203], v[98:101]
	v_mfma_f32_16x16x32_f16 v[94:97], v[160:163], v[200:203], v[94:97]
	v_mfma_f32_16x16x32_f16 v[82:85], v[148:151], v[218:221], v[82:85]
	v_mfma_f32_16x16x32_f16 v[78:81], v[160:163], v[218:221], v[78:81]
	v_mfma_f32_16x16x32_f16 v[122:125], v[164:167], v[180:183], v[122:125]
	v_mfma_f32_16x16x32_f16 v[118:121], v[172:175], v[180:183], v[118:121]
	v_mfma_f32_16x16x32_f16 v[106:109], v[164:167], v[188:191], v[106:109]
	v_mfma_f32_16x16x32_f16 v[102:105], v[172:175], v[188:191], v[102:105]
	v_mfma_f32_16x16x32_f16 v[90:93], v[164:167], v[196:199], v[90:93]
	v_mfma_f32_16x16x32_f16 v[86:89], v[172:175], v[196:199], v[86:89]
	v_mfma_f32_16x16x32_f16 v[74:77], v[164:167], v[204:207], v[74:77]
	v_mfma_f32_16x16x32_f16 v[70:73], v[172:175], v[204:207], v[70:73]
	v_mfma_f32_16x16x32_f16 v[122:125], v[168:171], v[184:187], v[122:125]
	v_mfma_f32_16x16x32_f16 v[118:121], v[176:179], v[184:187], v[118:121]
	v_mfma_f32_16x16x32_f16 v[106:109], v[168:171], v[192:195], v[106:109]
	v_mfma_f32_16x16x32_f16 v[102:105], v[176:179], v[192:195], v[102:105]
	v_mfma_f32_16x16x32_f16 v[90:93], v[168:171], v[200:203], v[90:93]
	v_mfma_f32_16x16x32_f16 v[86:89], v[176:179], v[200:203], v[86:89]
	v_mfma_f32_16x16x32_f16 v[74:77], v[168:171], v[218:221], v[74:77]
	v_mfma_f32_16x16x32_f16 v[70:73], v[176:179], v[218:221], v[70:73]
	s_barrier
; #define PG8_STAGE(bufoff, gbase, voff) do { _Pragma("unroll") for (int _i = 0; _i < 2; ++_i) \
;         __builtin_amdgcn_global_load_lds((const unsigned*)((const char*)(gbase) + (voff)[_i]), (PG8_LAS unsigned*)(lds + (bufoff) + ldsw + _i * 8192), 16, 0, 0); } while (0)
; #define PG8_LDA(dst, b, h) do { _Pragma("unroll") for (int m = 0; m < 4; ++m) _Pragma("unroll") for (int k = 0; k < 2; ++k) dst[m][k] = *(const PG8_LAS bf16x8*)(lds + PG8_SA(b, h) + aoff + m * 2048 + k * 1024); } while (0)
; #define PG8_MMA(ai, bj, At, Bt) do { __builtin_amdgcn_s_setprio(1); _Pragma("unroll") for (int m = 0; m < 4; ++m) _Pragma("unroll") for (int n = 0; n < 2; ++n) _Pragma("unroll") for (int k = 0; k < 2; ++k) \
;         acc[ai][bj][m][n] = __builtin_amdgcn_mfma_f32_16x16x32_f16(Bt[n][k], At[m][k], acc[ai][bj][m][n], 0, 0, 0); __builtin_amdgcn_s_setprio(0); } while (0)
; #define PG8_WAIT_V(n) asm volatile("s_waitcnt vmcnt(" #n ")" ::: "memory")
; #define PG8_WAIT_L(n) asm volatile("s_waitcnt lgkmcnt(" #n ")" ::: "memory")
; #define PG8_BAR __builtin_amdgcn_s_barrier()
; #define PG8_SCHED __builtin_amdgcn_sched_barrier(0)
; template <class Epi, class Sched, bool ALIGN_EPI = false, bool SP2 = false>
; __device__ __forceinline__ void gemm_phase(PG8_LAS unsigned char* lds, const Gemm g, const Sched& S, const Epi& E) {
;     ...
;             PG8_LDA(At, 1, 1); PG8_STAGE(PG8_SB(1, 0), b3, voffB); PG8_STAGE(PG8_SB(1, 1), b3 + hstep, voffB); PG8_STAGE(PG8_SA(1, 0), a3, voffA);
;             PG8_WAIT_V(8); PG8_WAIT_L(0); PG8_BAR; PG8_MMA(1, 0, At, B0); PG8_MMA(1, 1, At, B1); PG8_BAR; PG8_SCHED;
	s_add_i32 s12, s12, s5
	v_lshl_add_u64 v[152:153], v[152:153], 0, s[34:35]
	s_mov_b32 m0, s12
	ds_read_b128 v[180:183], v155 offset:49152
	ds_read_b128 v[184:187], v155 offset:50176
	ds_read_b128 v[188:191], v155 offset:51200
	ds_read_b128 v[192:195], v155 offset:52224
	ds_read_b128 v[196:199], v155 offset:53248
	ds_read_b128 v[200:203], v155 offset:54272
	ds_read_b128 v[204:207], v155 offset:55296
	ds_read_b128 v[218:221], v155 offset:56320
	global_load_lds_dwordx4 v[152:153], off
	s_add_i32 m0, s12, 0x2000
	s_add_u32 s22, s22, 0x40080
	v_lshl_add_u64 v[152:153], v[208:209], 0, s[34:35]
	s_addc_u32 s23, s23, 0
	s_add_i32 s12, s13, s5
	global_load_lds_dwordx4 v[152:153], off
	v_lshl_add_u64 v[152:153], s[22:23], 0, v[136:137]
	s_mov_b32 m0, s12
	s_nop 0
	global_load_lds_dwordx4 v[152:153], off
	v_lshl_add_u64 v[152:153], s[22:23], 0, v[14:15]
	s_add_i32 m0, s12, 0x2000
	s_nop 0
	global_load_lds_dwordx4 v[152:153], off
	v_lshl_add_u64 v[152:153], v[210:211], 0, s[34:35]
	s_mov_b32 m0, s29
	s_nop 0
	global_load_lds_dwordx4 v[152:153], off
	v_lshl_add_u64 v[152:153], v[212:213], 0, s[34:35]
	s_mov_b32 m0, s33
	s_nop 0
	global_load_lds_dwordx4 v[152:153], off
	s_waitcnt vmcnt(8)
	s_waitcnt lgkmcnt(0)
	s_barrier
	v_mfma_f32_16x16x32_f16 v[66:69], v[144:147], v[180:183], v[66:69]
	v_mfma_f32_16x16x32_f16 v[62:65], v[156:159], v[180:183], v[62:65]
	v_mfma_f32_16x16x32_f16 v[50:53], v[144:147], v[188:191], v[50:53]
	v_mfma_f32_16x16x32_f16 v[46:49], v[156:159], v[188:191], v[46:49]
	v_mfma_f32_16x16x32_f16 v[34:37], v[144:147], v[196:199], v[34:37]
	v_mfma_f32_16x16x32_f16 v[30:33], v[156:159], v[196:199], v[30:33]
	v_mfma_f32_16x16x32_f16 v[18:21], v[144:147], v[204:207], v[18:21]
	v_mfma_f32_16x16x32_f16 v[10:13], v[156:159], v[204:207], v[10:13]
	v_mfma_f32_16x16x32_f16 v[66:69], v[148:151], v[184:187], v[66:69]
	v_mfma_f32_16x16x32_f16 v[62:65], v[160:163], v[184:187], v[62:65]
	v_mfma_f32_16x16x32_f16 v[50:53], v[148:151], v[192:195], v[50:53]
	v_mfma_f32_16x16x32_f16 v[46:49], v[160:163], v[192:195], v[46:49]
	v_mfma_f32_16x16x32_f16 v[34:37], v[148:151], v[200:203], v[34:37]
	v_mfma_f32_16x16x32_f16 v[30:33], v[160:163], v[200:203], v[30:33]
	v_mfma_f32_16x16x32_f16 v[18:21], v[148:151], v[218:221], v[18:21]
	v_mfma_f32_16x16x32_f16 v[10:13], v[160:163], v[218:221], v[10:13]
	v_mfma_f32_16x16x32_f16 v[58:61], v[164:167], v[180:183], v[58:61]
	v_mfma_f32_16x16x32_f16 v[54:57], v[172:175], v[180:183], v[54:57]
	v_mfma_f32_16x16x32_f16 v[42:45], v[164:167], v[188:191], v[42:45]
	v_mfma_f32_16x16x32_f16 v[38:41], v[172:175], v[188:191], v[38:41]
	v_mfma_f32_16x16x32_f16 v[26:29], v[164:167], v[196:199], v[26:29]
	v_mfma_f32_16x16x32_f16 v[22:25], v[172:175], v[196:199], v[22:25]
	v_mfma_f32_16x16x32_f16 v[6:9], v[164:167], v[204:207], v[6:9]
	v_mfma_f32_16x16x32_f16 v[2:5], v[172:175], v[204:207], v[2:5]
	v_mfma_f32_16x16x32_f16 v[58:61], v[168:171], v[184:187], v[58:61]
	v_mfma_f32_16x16x32_f16 v[54:57], v[176:179], v[184:187], v[54:57]
	v_mfma_f32_16x16x32_f16 v[42:45], v[168:171], v[192:195], v[42:45]
	v_mfma_f32_16x16x32_f16 v[38:41], v[176:179], v[192:195], v[38:41]
	v_mfma_f32_16x16x32_f16 v[26:29], v[168:171], v[200:203], v[26:29]
	v_mfma_f32_16x16x32_f16 v[22:25], v[176:179], v[200:203], v[22:25]
	v_mfma_f32_16x16x32_f16 v[6:9], v[168:171], v[218:221], v[6:9]
	v_mfma_f32_16x16x32_f16 v[2:5], v[176:179], v[218:221], v[2:5]
	s_barrier
	s_add_i32 s82, s82, 2
	s_add_u32 s50, s50, 0x100
	s_addc_u32 s51, s51, 0
	s_add_u32 s76, s76, 0x100
	s_addc_u32 s77, s77, 0
	s_cmp_gt_u32 s82, 13
	s_cbranch_scc0 .LBB0_269
	s_and_b64 vcc, exec, s[14:15]
	s_cbranch_vccz .LBB0_272
	s_barrier
